# speedup vs baseline: 1.0119x; 1.0013x over previous
; __device__ void attn_item(const Params& p, int layer, int item, int dry) {
;     ...
;   const int tile = item >> 2, h = item & 3;
;   const int tok0 = tile * 128;
;   const int seq = tok0 < 32768 ? (tok0 >> 11) : 16 + ((tok0 - 32768) >> 12);
;   bf16_t* Ks = (bf16_t*)smem;
;   bf16_t* Vt = (bf16_t*)(smem + 256 * 72 * 2);
;   const bf16_t* kvs = kv + (size_t)seq * 256 * 1024;
;   for (int i = 0; i < 4; ++i) {
;     int idx = tid + 512 * i;
;     int m = idx >> 3, d0 = (idx & 7) * 8;
;     uint4 uk = *(const uint4*)(kvs + (size_t)m * 1024 + h * 64 + d0);
;     *(uint4*)(Ks + m * 72 + d0) = uk;
;     uint4 uv = *(const uint4*)(kvs + (size_t)m * 1024 + 256 + h * 64 + d0);
;     unsigned uu[4] = {uv.x, uv.y, uv.z, uv.w};
;     for (int j = 0; j < 8; ++j) Vt[(d0 + j) * 264 + m] = (bf16_t)((j & 1) ? (uu[j >> 1] >> 16) : (uu[j >> 1] & 0xffff));
;   }
;   __syncthreads();
;   const int t = tok0 + wid * 16 + r;
;   bf16_t* qp = cat + (size_t)t * 1024 + 768 + h * 64;
;   bf16x8 qf[2];
;   qf[0] = *(const bf16x8*)(qp + quad * 8);
;   qf[1] = *(const bf16x8*)(qp + 32 + quad * 8);
.LBB0_1348:
	s_and_b64 vcc, exec, s[4:5]
	s_cbranch_vccz .LBB0_1365
	s_lshl_b32 s4, s27, 5
	s_and_b32 s6, s4, 0xffffff80
	s_addk_i32 s4, 0x8000
	s_lshr_b32 s4, s4, 12
	s_ashr_i32 s5, s27, 6
	s_add_i32 s4, s4, 16
	s_cmp_lt_i32 s6, 0x8000
	v_mov_b32_e32 v44, v208
	s_cselect_b32 s4, s5, s4
	s_ashr_i32 s5, s4, 31
	v_add_u32_e32 v10, 0x200, v44
	v_add_u32_e32 v18, 0x400, v44
	v_add_u32_e32 v26, 0x600, v44
	s_lshl_b64 s[4:5], s[4:5], 19
	v_ashrrev_i32_e32 v34, 3, v44
	v_ashrrev_i32_e32 v36, 3, v10
	v_ashrrev_i32_e32 v38, 3, v18
	v_ashrrev_i32_e32 v40, 3, v26
	s_add_u32 s4, s77, s4
	v_ashrrev_i32_e32 v35, 31, v34
	v_ashrrev_i32_e32 v37, 31, v36
	v_ashrrev_i32_e32 v39, 31, v38
	v_ashrrev_i32_e32 v41, 31, v40
	s_addc_u32 s5, s78, s5
	v_lshlrev_b32_e32 v0, 3, v44
	v_lshlrev_b64 v[2:3], 11, v[34:35]
	s_lshl_b32 s7, s27, 7
	v_lshlrev_b64 v[10:11], 11, v[36:37]
	v_lshlrev_b64 v[18:19], 11, v[38:39]
	v_lshlrev_b64 v[26:27], 11, v[40:41]
	v_and_b32_e32 v42, 56, v0
	v_lshl_add_u64 v[2:3], s[4:5], 0, v[2:3]
	s_and_b32 s66, s7, 0x180
	v_lshl_add_u64 v[10:11], s[4:5], 0, v[10:11]
	v_lshl_add_u64 v[18:19], s[4:5], 0, v[18:19]
	v_lshl_add_u64 v[26:27], s[4:5], 0, v[26:27]
	v_lshlrev_b32_e32 v0, 1, v42
	v_lshl_add_u64 v[2:3], v[2:3], 0, s[66:67]
	v_lshl_add_u64 v[10:11], v[10:11], 0, s[66:67]
	v_lshl_add_u64 v[18:19], v[18:19], 0, s[66:67]
	v_lshl_add_u64 v[26:27], v[26:27], 0, s[66:67]
	v_lshl_add_u64 v[6:7], v[2:3], 0, v[0:1]
	v_lshl_add_u64 v[14:15], v[10:11], 0, v[0:1]
	v_lshl_add_u64 v[22:23], v[18:19], 0, v[0:1]
	v_lshl_add_u64 v[30:31], v[26:27], 0, v[0:1]
	global_load_dwordx4 v[2:5], v[6:7], off
	s_nop 0
	global_load_dwordx4 v[6:9], v[6:7], off offset:512
	s_nop 0
	global_load_dwordx4 v[10:13], v[14:15], off
	s_nop 0
	global_load_dwordx4 v[14:17], v[14:15], off offset:512
	s_nop 0
	global_load_dwordx4 v[18:21], v[22:23], off
	s_nop 0
	global_load_dwordx4 v[22:25], v[22:23], off offset:512
	s_nop 0
	global_load_dwordx4 v[26:29], v[30:31], off
	s_nop 0
	global_load_dwordx4 v[30:33], v[30:31], off offset:512
	s_movk_i32 s7, 0x90
	v_mul_u32_u24_e32 v41, 0x251, v42
	v_mad_u64_u32 v[42:43], s[4:5], v34, s7, v[0:1]
	v_lshl_add_u32 v43, v34, 1, v41
	v_mad_u64_u32 v[34:35], s[4:5], v36, s7, v[0:1]
	v_lshl_add_u32 v35, v36, 1, v41
	v_mad_u64_u32 v[36:37], s[4:5], v38, s7, v[0:1]
	v_lshl_add_u32 v37, v38, 1, v41
	v_mad_u64_u32 v[38:39], s[4:5], v40, s7, v[0:1]
	v_lshl_add_u32 v0, v40, 1, v41
	v_and_b32_e32 v60, 15, v44
	v_bfe_u32 v61, v44, 4, 2
	s_mov_b64 s[4:5], 0xe1a6600
	s_waitcnt vmcnt(7)
	ds_write_b128 v42, v[2:5]
	s_waitcnt vmcnt(6)
	ds_write_b16 v43, v6 offset:36864
	ds_write_b16_d16_hi v43, v6 offset:37456
	ds_write_b16 v43, v7 offset:38048
	ds_write_b16_d16_hi v43, v7 offset:38640
	ds_write_b16 v43, v8 offset:39232
	ds_write_b16_d16_hi v43, v8 offset:39824
	ds_write_b16 v43, v9 offset:40416
	ds_write_b16_d16_hi v43, v9 offset:41008
	s_waitcnt vmcnt(5)
	ds_write_b128 v34, v[10:13]
	s_waitcnt vmcnt(4)
	ds_write_b16 v35, v14 offset:36864
	ds_write_b16_d16_hi v35, v14 offset:37456
	ds_write_b16 v35, v15 offset:38048
	ds_write_b16_d16_hi v35, v15 offset:38640
	ds_write_b16 v35, v16 offset:39232
	ds_write_b16_d16_hi v35, v16 offset:39824
	ds_write_b16 v35, v17 offset:40416
	ds_write_b16_d16_hi v35, v17 offset:41008
	s_waitcnt vmcnt(3)
	ds_write_b128 v36, v[18:21]
	s_waitcnt vmcnt(2)
	ds_write_b16 v37, v22 offset:36864
	ds_write_b16_d16_hi v37, v22 offset:37456
	ds_write_b16 v37, v23 offset:38048
	ds_write_b16_d16_hi v37, v23 offset:38640
	ds_write_b16 v37, v24 offset:39232
	ds_write_b16_d16_hi v37, v24 offset:39824
	ds_write_b16 v37, v25 offset:40416
	ds_write_b16_d16_hi v37, v25 offset:41008
	s_waitcnt vmcnt(1)
	ds_write_b128 v38, v[26:29]
	s_waitcnt vmcnt(0)
	ds_write_b16 v0, v30 offset:36864
	ds_write_b16_d16_hi v0, v30 offset:37456
	ds_write_b16 v0, v31 offset:38048
	ds_write_b16_d16_hi v0, v31 offset:38640
	ds_write_b16 v0, v32 offset:39232
	ds_write_b16_d16_hi v0, v32 offset:39824
	ds_write_b16 v0, v33 offset:40416
	ds_write_b16_d16_hi v0, v33 offset:41008
	v_ashrrev_i32_e32 v0, 2, v44
	v_and_b32_e32 v0, -16, v0
	v_add_u32_e32 v0, s6, v0
	v_or_b32_e32 v2, v0, v60
	v_ashrrev_i32_e32 v3, 31, v2
	v_lshlrev_b64 v[2:3], 11, v[2:3]
	v_lshl_add_u64 v[2:3], s[14:15], 0, v[2:3]
	v_lshl_add_u64 v[2:3], v[2:3], 0, s[66:67]
	v_lshl_add_u64 v[54:55], v[2:3], 0, s[4:5]
	v_lshlrev_b32_e32 v0, 4, v61
	v_lshl_add_u64 v[34:35], v[54:55], 0, v[0:1]
	global_load_dwordx4 v[2:5], v[34:35], off
	global_load_dwordx4 v[56:59], v[34:35], off offset:64
	s_waitcnt lgkmcnt(0)
	s_barrier
; __device__ void attn_item(const Params& p, int layer, int item, int dry) {
;     ...
;   f32x4 s[16];
;   for (int mt = 0; mt < 16; ++mt) {
;     s[mt] = f32x4{0.f, 0.f, 0.f, 0.f};
;     for (int ks = 0; ks < 2; ++ks) {
;       bf16x8 a = *(const bf16x8*)(Ks + (mt * 16 + r) * 72 + ks * 32 + quad * 8);
;       s[mt] = __builtin_amdgcn_mfma_f32_16x16x32_bf16(a, qf[ks], s[mt], 0, 0, 0);
;     }
;   }
;   float mx = -1e30f;
;   for (int mt = 0; mt < 16; ++mt)
;     for (int j = 0; j < 4; ++j) mx = fmaxf(mx, s[mt][j]);
;   mx = fmaxf(mx, __shfl_xor(mx, 16));
;   mx = fmaxf(mx, __shfl_xor(mx, 32));
	v_mad_u32_u24 v98, v60, s7, v0
	ds_read_b128 v[38:41], v98 offset:18432
	ds_read_b128 v[6:9], v98
	ds_read_b128 v[10:13], v98 offset:2304
	ds_read_b128 v[14:17], v98 offset:4608
	ds_read_b128 v[18:21], v98 offset:6912
	ds_read_b128 v[22:25], v98 offset:9216
	ds_read_b128 v[26:29], v98 offset:11520
	ds_read_b128 v[30:33], v98 offset:13824
	ds_read_b128 v[34:37], v98 offset:16128
	s_mov_b32 s4, 0xf149f2ca
	s_waitcnt vmcnt(1) lgkmcnt(8)
	s_setprio 1
	v_mfma_f32_16x16x32_bf16 v[62:65], v[38:41], v[2:5], 0
	ds_read_b128 v[38:41], v98 offset:20736
	s_waitcnt lgkmcnt(0)
	v_mfma_f32_16x16x32_bf16 v[66:69], v[38:41], v[2:5], 0
	ds_read_b128 v[38:41], v98 offset:23040
	s_waitcnt lgkmcnt(0)
	v_mfma_f32_16x16x32_bf16 v[70:73], v[38:41], v[2:5], 0
	ds_read_b128 v[38:41], v98 offset:25344
	s_waitcnt lgkmcnt(0)
	v_mfma_f32_16x16x32_bf16 v[74:77], v[38:41], v[2:5], 0
	ds_read_b128 v[38:41], v98 offset:27648
	s_waitcnt lgkmcnt(0)
	v_mfma_f32_16x16x32_bf16 v[78:81], v[38:41], v[2:5], 0
	ds_read_b128 v[38:41], v98 offset:29952
	s_waitcnt lgkmcnt(0)
	v_mfma_f32_16x16x32_bf16 v[82:85], v[38:41], v[2:5], 0
	ds_read_b128 v[38:41], v98 offset:64
	v_mfma_f32_16x16x32_bf16 v[6:9], v[6:9], v[2:5], 0
	s_waitcnt vmcnt(0) lgkmcnt(0)
	v_mfma_f32_16x16x32_bf16 v[86:89], v[38:41], v[56:59], v[6:9]
	s_nop 5
	ds_read_b128 v[6:9], v98 offset:2368
	v_mfma_f32_16x16x32_bf16 v[10:13], v[10:13], v[2:5], 0
	s_waitcnt lgkmcnt(0)
	v_mfma_f32_16x16x32_bf16 v[90:93], v[6:9], v[56:59], v[10:13]
	ds_read_b128 v[6:9], v98 offset:4672
	v_mfma_f32_16x16x32_bf16 v[14:17], v[14:17], v[2:5], 0
	s_waitcnt lgkmcnt(0)
	v_mfma_f32_16x16x32_bf16 v[94:97], v[6:9], v[56:59], v[14:17]
	ds_read_b128 v[6:9], v98 offset:6976
	v_mfma_f32_16x16x32_bf16 v[18:21], v[18:21], v[2:5], 0
	s_waitcnt lgkmcnt(0)
	v_mfma_f32_16x16x32_bf16 v[50:53], v[6:9], v[56:59], v[18:21]
	ds_read_b128 v[6:9], v98 offset:9280
	v_mfma_f32_16x16x32_bf16 v[22:25], v[22:25], v[2:5], 0
	s_waitcnt lgkmcnt(0)
	v_mfma_f32_16x16x32_bf16 v[46:49], v[6:9], v[56:59], v[22:25]
	ds_read_b128 v[6:9], v98 offset:11584
	v_mfma_f32_16x16x32_bf16 v[26:29], v[26:29], v[2:5], 0
	s_waitcnt lgkmcnt(0)
	v_mfma_f32_16x16x32_bf16 v[42:45], v[6:9], v[56:59], v[26:29]
	ds_read_b128 v[6:9], v98 offset:13888
	v_mfma_f32_16x16x32_bf16 v[30:33], v[30:33], v[2:5], 0
	s_waitcnt lgkmcnt(0)
	v_mfma_f32_16x16x32_bf16 v[38:41], v[6:9], v[56:59], v[30:33]
	ds_read_b128 v[6:9], v98 offset:16192
	v_mfma_f32_16x16x32_bf16 v[34:37], v[34:37], v[2:5], 0
	s_waitcnt lgkmcnt(0)
	v_mfma_f32_16x16x32_bf16 v[34:37], v[6:9], v[56:59], v[34:37]
	ds_read_b128 v[6:9], v98 offset:18496
	s_waitcnt lgkmcnt(0)
	v_mfma_f32_16x16x32_bf16 v[30:33], v[6:9], v[56:59], v[62:65]
	ds_read_b128 v[6:9], v98 offset:20800
	s_nop 1
	ds_read_b128 v[62:65], v98 offset:32320
	s_waitcnt lgkmcnt(1)
	v_mfma_f32_16x16x32_bf16 v[26:29], v[6:9], v[56:59], v[66:69]
	ds_read_b128 v[6:9], v98 offset:23104
	s_waitcnt lgkmcnt(0)
	v_mfma_f32_16x16x32_bf16 v[22:25], v[6:9], v[56:59], v[70:73]
	ds_read_b128 v[6:9], v98 offset:25408
	s_waitcnt lgkmcnt(0)
	v_mfma_f32_16x16x32_bf16 v[18:21], v[6:9], v[56:59], v[74:77]
	ds_read_b128 v[6:9], v98 offset:27712
	s_waitcnt lgkmcnt(0)
	v_mfma_f32_16x16x32_bf16 v[14:17], v[6:9], v[56:59], v[78:81]
	ds_read_b128 v[6:9], v98 offset:30016
	s_waitcnt lgkmcnt(0)
	v_mfma_f32_16x16x32_bf16 v[10:13], v[6:9], v[56:59], v[82:85]
	ds_read_b128 v[6:9], v98 offset:32256
	s_waitcnt lgkmcnt(0)
	v_mfma_f32_16x16x32_bf16 v[6:9], v[6:9], v[2:5], 0
	v_mfma_f32_16x16x32_bf16 v[6:9], v[62:65], v[56:59], v[6:9]
	ds_read_b128 v[62:65], v98 offset:34560
	s_waitcnt lgkmcnt(0)
	v_mfma_f32_16x16x32_bf16 v[2:5], v[62:65], v[2:5], 0
	ds_read_b128 v[62:65], v98 offset:34624
	s_waitcnt lgkmcnt(0)
	v_mfma_f32_16x16x32_bf16 v[2:5], v[62:65], v[56:59], v[2:5]
	s_setprio 0
	v_max3_f32 v56, v86, s4, v87
	v_max3_f32 v56, v56, v88, v89
	v_max3_f32 v56, v56, v90, v91
	v_max3_f32 v56, v56, v92, v93
	v_max3_f32 v56, v56, v94, v95
	v_max3_f32 v56, v56, v96, v97
	v_max3_f32 v56, v56, v50, v51
	v_max3_f32 v56, v56, v52, v53
	v_max3_f32 v56, v56, v46, v47
	v_max3_f32 v56, v56, v48, v49
	v_max3_f32 v56, v56, v42, v43
	v_max3_f32 v56, v56, v44, v45
	v_max3_f32 v56, v56, v38, v39
	v_max3_f32 v56, v56, v40, v41
	v_max3_f32 v56, v56, v34, v35
	v_max3_f32 v56, v56, v36, v37
	v_max3_f32 v56, v56, v30, v31
	v_max3_f32 v56, v56, v32, v33
	v_max3_f32 v56, v56, v26, v27
	v_max3_f32 v56, v56, v28, v29
	v_max3_f32 v56, v56, v22, v23
	v_max3_f32 v56, v56, v24, v25
	v_max3_f32 v56, v56, v18, v19
	v_max3_f32 v56, v56, v20, v21
	v_max3_f32 v56, v56, v14, v15
	v_max3_f32 v56, v56, v16, v17
	v_max3_f32 v56, v56, v10, v11
	v_max3_f32 v56, v56, v12, v13
	v_and_b32_e32 v58, 64, v228
	v_max3_f32 v56, v56, v6, v7
	v_xor_b32_e32 v57, 16, v228
	v_add_u32_e32 v59, 64, v58
	v_max3_f32 v56, v56, v8, v9
	v_cmp_lt_i32_e32 vcc, v57, v59
	v_max3_f32 v56, v56, v2, v3
	v_max3_f32 v56, v56, v4, v5
	v_cndmask_b32_e32 v57, v228, v57, vcc
	v_lshlrev_b32_e32 v58, 2, v57
	ds_bpermute_b32 v57, v58, v56
	s_movk_i32 s4, 0x210
	s_waitcnt lgkmcnt(0)
	v_max_f32_e32 v57, v57, v57
	v_max_f32_e32 v62, v56, v57
	v_xor_b32_e32 v56, 32, v228
	v_cmp_lt_i32_e32 vcc, v56, v59
	s_nop 1
	v_cndmask_b32_e32 v56, v228, v56, vcc
	v_lshlrev_b32_e32 v57, 2, v56
	ds_bpermute_b32 v59, v57, v62
	v_lshlrev_b32_e32 v56, 3, v61
	v_sub_u32_e32 v0, v0, v56
	s_andn2_b64 vcc, exec, s[24:25]
	s_waitcnt lgkmcnt(0)
; __device__ void attn_item(const Params& p, int layer, int item, int dry) {
;     ...
;   float sum = 0.f;
;   for (int mt = 0; mt < 16; ++mt)
;     for (int j = 0; j < 4; ++j) {
;       float e = __expf((s[mt][j] - mx) * 0.125f);
;       s[mt][j] = e;
;       sum += e;
;     }
	v_max_f32_e32 v59, v59, v59
	v_max_f32_e32 v59, v62, v59
	v_sub_f32_e32 v61, v86, v59
	v_mul_f32_e32 v61, 0x3e38aa3b, v61
	v_exp_f32_e32 v65, v61
	v_sub_f32_e32 v61, v87, v59
	v_mul_f32_e32 v61, 0x3e38aa3b, v61
	v_sub_f32_e32 v62, v90, v59
	v_mul_f32_e32 v62, 0x3e38aa3b, v62
	v_exp_f32_e32 v66, v61
	v_sub_f32_e32 v61, v88, v59
	v_mul_f32_e32 v61, 0x3e38aa3b, v61
	v_exp_f32_e32 v68, v62
	v_sub_f32_e32 v62, v91, v59
	v_mul_f32_e32 v62, 0x3e38aa3b, v62
	v_exp_f32_e32 v67, v61
	v_sub_f32_e32 v61, v89, v59
	v_mul_f32_e32 v61, 0x3e38aa3b, v61
	v_exp_f32_e32 v75, v62
	v_sub_f32_e32 v62, v92, v59
	v_mul_f32_e32 v62, 0x3e38aa3b, v62
	v_exp_f32_e32 v74, v61
	v_add_f32_e32 v61, 0, v65
	v_exp_f32_e32 v69, v62
	v_sub_f32_e32 v62, v93, v59
	v_add_f32_e32 v61, v66, v61
	v_mul_f32_e32 v62, 0x3e38aa3b, v62
	v_add_f32_e32 v61, v67, v61
	v_add_f32_e32 v61, v74, v61
	v_exp_f32_e32 v70, v62
	v_add_f32_e32 v61, v68, v61
	v_add_f32_e32 v61, v75, v61
	v_sub_f32_e32 v50, v50, v59
	v_add_f32_e32 v61, v69, v61
	v_mul_f32_e32 v50, 0x3e38aa3b, v50
	v_add_f32_e32 v71, v70, v61
	v_sub_f32_e32 v61, v94, v59
	v_mul_f32_e32 v61, 0x3e38aa3b, v61
	v_sub_f32_e32 v62, v95, v59
	v_exp_f32_e32 v90, v50
	v_sub_f32_e32 v50, v51, v59
	v_mul_f32_e32 v62, 0x3e38aa3b, v62
	v_sub_f32_e32 v63, v96, v59
	v_mul_f32_e32 v50, 0x3e38aa3b, v50
	v_exp_f32_e32 v61, v61
	v_mul_f32_e32 v63, 0x3e38aa3b, v63
	v_sub_f32_e32 v64, v97, v59
	v_exp_f32_e32 v62, v62
	v_mul_f32_e32 v64, 0x3e38aa3b, v64
	v_exp_f32_e32 v91, v50
	v_sub_f32_e32 v50, v52, v59
	v_exp_f32_e32 v63, v63
	v_mul_f32_e32 v50, 0x3e38aa3b, v50
	v_exp_f32_e32 v64, v64
	v_add_f32_e32 v71, v61, v71
	v_exp_f32_e32 v92, v50
	v_sub_f32_e32 v50, v53, v59
	v_add_f32_e32 v71, v62, v71
	v_mul_f32_e32 v50, 0x3e38aa3b, v50
	v_sub_f32_e32 v46, v46, v59
	v_add_f32_e32 v71, v63, v71
	v_mul_f32_e32 v46, 0x3e38aa3b, v46
	v_sub_f32_e32 v47, v47, v59
	v_add_f32_e32 v71, v64, v71
	v_exp_f32_e32 v53, v50
	v_mul_f32_e32 v47, 0x3e38aa3b, v47
	v_sub_f32_e32 v48, v48, v59
	v_add_f32_e32 v50, v90, v71
	v_exp_f32_e32 v46, v46
	v_mul_f32_e32 v48, 0x3e38aa3b, v48
	v_sub_f32_e32 v49, v49, v59
	v_add_f32_e32 v50, v91, v50
	v_exp_f32_e32 v47, v47
	v_mul_f32_e32 v49, 0x3e38aa3b, v49
	v_add_f32_e32 v50, v92, v50
	v_exp_f32_e32 v48, v48
	v_add_f32_e32 v50, v53, v50
	v_exp_f32_e32 v49, v49
	v_add_f32_e32 v50, v46, v50
	v_sub_f32_e32 v42, v42, v59
	v_add_f32_e32 v50, v47, v50
	v_mul_f32_e32 v42, 0x3e38aa3b, v42
	v_add_f32_e32 v50, v48, v50
	v_add_f32_e32 v71, v49, v50
	v_exp_f32_e32 v50, v42
	v_sub_f32_e32 v42, v43, v59
	v_mul_f32_e32 v42, 0x3e38aa3b, v42
	v_exp_f32_e32 v51, v42
	v_sub_f32_e32 v42, v44, v59
	v_mul_f32_e32 v42, 0x3e38aa3b, v42
	v_exp_f32_e32 v52, v42
	v_sub_f32_e32 v42, v45, v59
	v_mul_f32_e32 v42, 0x3e38aa3b, v42
	v_sub_f32_e32 v38, v38, v59
	v_mul_f32_e32 v38, 0x3e38aa3b, v38
	v_sub_f32_e32 v39, v39, v59
	v_exp_f32_e32 v45, v42
	v_mul_f32_e32 v39, 0x3e38aa3b, v39
	v_sub_f32_e32 v40, v40, v59
	v_add_f32_e32 v42, v50, v71
	v_exp_f32_e32 v38, v38
	v_mul_f32_e32 v40, 0x3e38aa3b, v40
	v_sub_f32_e32 v41, v41, v59
	v_add_f32_e32 v42, v51, v42
	v_exp_f32_e32 v39, v39
	v_mul_f32_e32 v41, 0x3e38aa3b, v41
	v_add_f32_e32 v42, v52, v42
	v_exp_f32_e32 v40, v40
	v_add_f32_e32 v42, v45, v42
	v_exp_f32_e32 v41, v41
	v_add_f32_e32 v42, v38, v42
	v_sub_f32_e32 v34, v34, v59
	v_add_f32_e32 v42, v39, v42
	v_mul_f32_e32 v34, 0x3e38aa3b, v34
	v_add_f32_e32 v42, v40, v42
	v_add_f32_e32 v71, v41, v42
	v_exp_f32_e32 v42, v34
	v_sub_f32_e32 v34, v35, v59
	v_mul_f32_e32 v34, 0x3e38aa3b, v34
	v_exp_f32_e32 v43, v34
	v_sub_f32_e32 v34, v36, v59
	v_mul_f32_e32 v34, 0x3e38aa3b, v34
	v_exp_f32_e32 v44, v34
	v_sub_f32_e32 v34, v37, v59
	v_mul_f32_e32 v34, 0x3e38aa3b, v34
	v_sub_f32_e32 v30, v30, v59
	v_mul_f32_e32 v30, 0x3e38aa3b, v30
	v_sub_f32_e32 v31, v31, v59
	v_exp_f32_e32 v37, v34
	v_mul_f32_e32 v31, 0x3e38aa3b, v31
	v_sub_f32_e32 v32, v32, v59
	v_add_f32_e32 v34, v42, v71
	v_exp_f32_e32 v30, v30
	v_mul_f32_e32 v32, 0x3e38aa3b, v32
	v_sub_f32_e32 v33, v33, v59
	v_add_f32_e32 v34, v43, v34
	v_exp_f32_e32 v31, v31
	v_mul_f32_e32 v33, 0x3e38aa3b, v33
	v_add_f32_e32 v34, v44, v34
	v_exp_f32_e32 v32, v32
	v_add_f32_e32 v34, v37, v34
	v_exp_f32_e32 v33, v33
	v_add_f32_e32 v34, v30, v34
	v_sub_f32_e32 v26, v26, v59
	v_add_f32_e32 v34, v31, v34
	v_mul_f32_e32 v26, 0x3e38aa3b, v26
	v_add_f32_e32 v34, v32, v34
	v_add_f32_e32 v71, v33, v34
	v_exp_f32_e32 v34, v26
	v_sub_f32_e32 v26, v27, v59
	v_mul_f32_e32 v26, 0x3e38aa3b, v26
	v_exp_f32_e32 v35, v26
	v_sub_f32_e32 v26, v28, v59
	v_mul_f32_e32 v26, 0x3e38aa3b, v26
	v_exp_f32_e32 v28, v26
	v_sub_f32_e32 v26, v29, v59
	v_mul_f32_e32 v26, 0x3e38aa3b, v26
	v_sub_f32_e32 v22, v22, v59
	v_mul_f32_e32 v22, 0x3e38aa3b, v22
	v_sub_f32_e32 v23, v23, v59
	v_exp_f32_e32 v36, v26
	v_mul_f32_e32 v23, 0x3e38aa3b, v23
	v_sub_f32_e32 v24, v24, v59
	v_add_f32_e32 v26, v34, v71
	v_exp_f32_e32 v22, v22
	v_mul_f32_e32 v24, 0x3e38aa3b, v24
	v_sub_f32_e32 v25, v25, v59
	v_add_f32_e32 v26, v35, v26
	v_exp_f32_e32 v23, v23
	v_mul_f32_e32 v25, 0x3e38aa3b, v25
	v_add_f32_e32 v26, v28, v26
	v_exp_f32_e32 v24, v24
	v_add_f32_e32 v26, v36, v26
	v_exp_f32_e32 v25, v25
	v_add_f32_e32 v26, v22, v26
	v_sub_f32_e32 v18, v18, v59
	v_sub_f32_e32 v20, v20, v59
	v_add_f32_e32 v26, v23, v26
	v_mul_f32_e32 v18, 0x3e38aa3b, v18
	v_sub_f32_e32 v19, v19, v59
	v_mul_f32_e32 v20, 0x3e38aa3b, v20
	v_add_f32_e32 v26, v24, v26
	v_mul_f32_e32 v19, 0x3e38aa3b, v19
	v_add_f32_e32 v29, v25, v26
	v_exp_f32_e32 v18, v18
	v_exp_f32_e32 v26, v20
	v_sub_f32_e32 v20, v21, v59
	v_exp_f32_e32 v19, v19
	v_mul_f32_e32 v20, 0x3e38aa3b, v20
	v_sub_f32_e32 v14, v14, v59
	v_mul_f32_e32 v14, 0x3e38aa3b, v14
; __device__ __forceinline__ unsigned short f2bf(float f) { return (unsigned short)(pack2(f, 0.f) & 0xffffu); }
; __device__ void attn_item(const Params& p, int layer, int item, int dry) {
;     ...
;   float sum = 0.f;
;   for (int mt = 0; mt < 16; ++mt)
;     for (int j = 0; j < 4; ++j) {
;       float e = __expf((s[mt][j] - mx) * 0.125f);
;       s[mt][j] = e;
;       sum += e;
;     }
;   sum += __shfl_xor(sum, 16);
;   sum += __shfl_xor(sum, 32);
;   const float inv = 1.f / sum;
;   f32x4 o[4] = {};
;   for (int ks = 0; ks < 8; ++ks) {
;     bf16x8 pb;
;     for (int j = 0; j < 4; ++j) {
;       pb[j] = (short)f2bf(s[2 * ks][j]);
;       pb[4 + j] = (short)f2bf(s[2 * ks + 1][j]);
;     }
;     for (int dt = 0; dt < 4; ++dt) {
;       const bf16_t* vp = Vt + (dt * 16 + r) * 264 + ks * 32 + quad * 4;
;       uint2 v0 = *(const uint2*)vp, v1 = *(const uint2*)(vp + 16);
;       bf16x8 av;
;       av[0] = (short)(v0.x & 0xffff); av[1] = (short)(v0.x >> 16); av[2] = (short)(v0.y & 0xffff); av[3] = (short)(v0.y >> 16);
;       av[4] = (short)(v1.x & 0xffff); av[5] = (short)(v1.x >> 16); av[6] = (short)(v1.y & 0xffff); av[7] = (short)(v1.y >> 16);
;       o[dt] = __builtin_amdgcn_mfma_f32_16x16x32_bf16(av, pb, o[dt], 0, 0, 0);
;     }
;   }
	v_sub_f32_e32 v15, v15, v59
	v_exp_f32_e32 v27, v20
	v_mul_f32_e32 v15, 0x3e38aa3b, v15
	v_sub_f32_e32 v16, v16, v59
	v_add_f32_e32 v20, v18, v29
	v_exp_f32_e32 v14, v14
	v_mul_f32_e32 v16, 0x3e38aa3b, v16
	v_sub_f32_e32 v17, v17, v59
	v_add_f32_e32 v20, v19, v20
	v_exp_f32_e32 v15, v15
	v_mul_f32_e32 v17, 0x3e38aa3b, v17
	v_sub_f32_e32 v10, v10, v59
	v_add_f32_e32 v20, v26, v20
	v_exp_f32_e32 v16, v16
	v_mul_f32_e32 v10, 0x3e38aa3b, v10
	v_sub_f32_e32 v11, v11, v59
	v_add_f32_e32 v20, v27, v20
	v_exp_f32_e32 v17, v17
	v_mul_f32_e32 v11, 0x3e38aa3b, v11
	v_sub_f32_e32 v12, v12, v59
	v_add_f32_e32 v20, v14, v20
	v_exp_f32_e32 v10, v10
	v_mul_f32_e32 v12, 0x3e38aa3b, v12
	v_sub_f32_e32 v13, v13, v59
	v_add_f32_e32 v20, v15, v20
	v_exp_f32_e32 v11, v11
	v_mul_f32_e32 v13, 0x3e38aa3b, v13
	v_add_f32_e32 v20, v16, v20
	v_exp_f32_e32 v12, v12
	v_add_f32_e32 v20, v17, v20
	v_exp_f32_e32 v13, v13
	v_add_f32_e32 v20, v10, v20
	v_add_f32_e32 v20, v11, v20
	v_add_f32_e32 v20, v12, v20
	v_add_f32_e32 v86, v13, v20
	v_sub_f32_e32 v7, v7, v59
	v_mul_u32_u24_e32 v176, 0x250, v60
	v_lshrrev_b32_e32 v177, 3, v60
	v_add_u32_e32 v20, v176, v0
	v_lshl_add_u32 v20, v177, 3, v20
	v_mul_f32_e32 v29, 0x3e38aa3b, v7
	v_add_u32_e32 v21, 0x9000, v20
	v_add_u32_e32 v7, 0xb410, v20
	v_add_u32_e32 v0, 0xd820, v20
	v_add_u32_e32 v20, 0xfc30, v20
	v_cvt_pk_bf16_f32 v69, v69, v70
	ds_read2_b64 v[70:73], v21 offset1:4
	v_cvt_pk_bf16_f32 v68, v68, v75
	v_cvt_pk_bf16_f32 v67, v67, v74
	ds_read2_b64 v[74:77], v7 offset0:32 offset1:36
	ds_read2_b64 v[78:81], v0 offset0:64 offset1:68
	ds_read2_b64 v[82:85], v20 offset0:96 offset1:100
	v_sub_f32_e32 v6, v6, v59
	v_mul_f32_e32 v6, 0x3e38aa3b, v6
	v_exp_f32_e32 v6, v6
	s_waitcnt lgkmcnt(3)
	s_waitcnt lgkmcnt(2)
	s_waitcnt lgkmcnt(1)
	s_waitcnt lgkmcnt(0)
	v_exp_f32_e32 v29, v29
	v_cvt_pk_bf16_f32 v66, v65, v66
	v_add_f32_e32 v60, v6, v86
	ds_read2_b64 v[86:89], v21 offset0:8 offset1:12
	s_setprio 1
	v_mfma_f32_16x16x32_bf16 v[70:73], v[70:73], v[66:69], 0
	v_add_f32_e32 v94, v29, v60
	v_sub_f32_e32 v8, v8, v59
	v_mul_f32_e32 v8, 0x3e38aa3b, v8
	v_mfma_f32_16x16x32_bf16 v[74:77], v[74:77], v[66:69], 0
	s_waitcnt lgkmcnt(0)
	v_sub_f32_e32 v2, v2, v59
	v_mfma_f32_16x16x32_bf16 v[78:81], v[78:81], v[66:69], 0
	v_mul_f32_e32 v2, 0x3e38aa3b, v2
	v_cvt_pk_bf16_f32 v27, v26, v27
	v_mfma_f32_16x16x32_bf16 v[66:69], v[82:85], v[66:69], 0
	v_cvt_pk_bf16_f32 v83, v63, v64
	v_cvt_pk_bf16_f32 v82, v61, v62
	ds_read2_b64 v[60:63], v0 offset0:72 offset1:76
	v_cvt_pk_bf16_f32 v85, v92, v53
	v_cvt_pk_bf16_f32 v84, v90, v91
	ds_read2_b64 v[90:93], v7 offset0:40 offset1:44
	v_cvt_pk_bf16_f32 v53, v52, v45
	s_waitcnt lgkmcnt(1)
	v_mfma_f32_16x16x32_bf16 v[70:73], v[86:89], v[82:85], v[70:73]
	ds_read2_b64 v[86:89], v20 offset0:104 offset1:108
	v_cvt_pk_bf16_f32 v52, v50, v51
	v_cvt_pk_bf16_f32 v51, v48, v49
	v_mfma_f32_16x16x32_bf16 v[60:63], v[60:63], v[82:85], v[78:81]
	v_cvt_pk_bf16_f32 v50, v46, v47
	ds_read2_b64 v[46:49], v0 offset0:80 offset1:84
	s_waitcnt lgkmcnt(2)
	ds_read2_b64 v[78:81], v21 offset0:16 offset1:20
	s_waitcnt lgkmcnt(2)
	v_mfma_f32_16x16x32_bf16 v[74:77], v[90:93], v[82:85], v[74:77]
	s_waitcnt lgkmcnt(0)
	v_cvt_pk_bf16_f32 v45, v44, v37
	v_mfma_f32_16x16x32_bf16 v[64:67], v[86:89], v[82:85], v[66:69]
	ds_read2_b64 v[82:85], v7 offset0:48 offset1:52
	v_cvt_pk_bf16_f32 v44, v42, v43
	v_cvt_pk_bf16_f32 v43, v40, v41
	v_mfma_f32_16x16x32_bf16 v[68:71], v[78:81], v[50:53], v[70:73]
	ds_read2_b64 v[78:81], v20 offset0:112 offset1:116
	v_cvt_pk_bf16_f32 v42, v38, v39
	ds_read2_b64 v[38:41], v0 offset0:88 offset1:92
	v_mfma_f32_16x16x32_bf16 v[46:49], v[46:49], v[50:53], v[60:63]
	s_waitcnt lgkmcnt(2)
	s_waitcnt lgkmcnt(1)
	v_cvt_pk_bf16_f32 v37, v28, v36
	ds_read2_b64 v[60:63], v21 offset0:24 offset1:28
	s_waitcnt lgkmcnt(1)
	v_mfma_f32_16x16x32_bf16 v[72:75], v[82:85], v[50:53], v[74:77]
	v_cvt_pk_bf16_f32 v36, v34, v35
	v_cvt_pk_bf16_f32 v35, v32, v33
	s_waitcnt lgkmcnt(0)
	v_mfma_f32_16x16x32_bf16 v[50:53], v[78:81], v[50:53], v[64:67]
	v_cvt_pk_bf16_f32 v34, v30, v31
	ds_read2_b64 v[30:33], v0 offset0:96 offset1:100
	v_exp_f32_e32 v90, v8
	ds_read2_b64 v[64:67], v7 offset0:56 offset1:60
	v_mfma_f32_16x16x32_bf16 v[60:63], v[60:63], v[42:45], v[68:71]
	v_sub_f32_e32 v8, v9, v59
	s_waitcnt lgkmcnt(1)
	v_mul_f32_e32 v8, 0x3e38aa3b, v8
	ds_read2_b64 v[68:71], v20 offset0:120 offset1:124
	v_mfma_f32_16x16x32_bf16 v[38:41], v[38:41], v[42:45], v[46:49]
	s_waitcnt lgkmcnt(1)
	v_exp_f32_e32 v9, v2
	ds_read2_b64 v[46:49], v21 offset0:32 offset1:36
	s_waitcnt lgkmcnt(1)
; __device__ __forceinline__ unsigned short f2bf(float f) { return (unsigned short)(pack2(f, 0.f) & 0xffffu); }
; __device__ void attn_item(const Params& p, int layer, int item, int dry) {
;     ...
;   sum += __shfl_xor(sum, 16);
;   sum += __shfl_xor(sum, 32);
;   const float inv = 1.f / sum;
;   f32x4 o[4] = {};
;   for (int ks = 0; ks < 8; ++ks) {
;     bf16x8 pb;
;     for (int j = 0; j < 4; ++j) {
;       pb[j] = (short)f2bf(s[2 * ks][j]);
;       pb[4 + j] = (short)f2bf(s[2 * ks + 1][j]);
;     }
;     for (int dt = 0; dt < 4; ++dt) {
;       const bf16_t* vp = Vt + (dt * 16 + r) * 264 + ks * 32 + quad * 4;
;       uint2 v0 = *(const uint2*)vp, v1 = *(const uint2*)(vp + 16);
;       bf16x8 av;
;       av[0] = (short)(v0.x & 0xffff); av[1] = (short)(v0.x >> 16); av[2] = (short)(v0.y & 0xffff); av[3] = (short)(v0.y >> 16);
;       av[4] = (short)(v1.x & 0xffff); av[5] = (short)(v1.x >> 16); av[6] = (short)(v1.y & 0xffff); av[7] = (short)(v1.y >> 16);
;       o[dt] = __builtin_amdgcn_mfma_f32_16x16x32_bf16(av, pb, o[dt], 0, 0, 0);
;     }
;   }
;   for (int dt = 0; dt < 4; ++dt) {
;     uint2 ov;
;     ov.x = pack2(o[dt][0] * inv, o[dt][1] * inv);
;     ov.y = pack2(o[dt][2] * inv, o[dt][3] * inv);
;     if (!dry) *(uint2*)(qp + dt * 16 + quad * 4) = ov;
;   }
	v_mfma_f32_16x16x32_bf16 v[64:67], v[64:67], v[42:45], v[72:75]
	v_sub_f32_e32 v2, v3, v59
	v_exp_f32_e32 v76, v8
	s_waitcnt lgkmcnt(0)
	v_mfma_f32_16x16x32_bf16 v[42:45], v[68:71], v[42:45], v[50:53]
	v_mul_f32_e32 v2, 0x3e38aa3b, v2
	v_exp_f32_e32 v28, v2
	ds_read2_b64 v[50:53], v7 offset0:64 offset1:68
	v_mfma_f32_16x16x32_bf16 v[46:49], v[46:49], v[34:37], v[60:63]
	v_add_f32_e32 v8, v90, v94
	v_add_f32_e32 v8, v76, v8
	v_add_f32_e32 v2, v9, v8
	ds_read2_b64 v[60:63], v20 offset0:128 offset1:132
	v_mfma_f32_16x16x32_bf16 v[30:33], v[30:33], v[34:37], v[38:41]
	s_waitcnt lgkmcnt(1)
	v_add_f32_e32 v8, v28, v2
	v_sub_f32_e32 v2, v4, v59
	ds_read2_b64 v[38:41], v21 offset0:40 offset1:44
	s_waitcnt lgkmcnt(1)
	v_mfma_f32_16x16x32_bf16 v[50:53], v[50:53], v[34:37], v[64:67]
	v_mul_f32_e32 v2, 0x3e38aa3b, v2
	s_waitcnt lgkmcnt(0)
	v_mfma_f32_16x16x32_bf16 v[34:37], v[60:63], v[34:37], v[42:45]
	ds_read2_b64 v[60:63], v0 offset0:104 offset1:108
	v_cvt_pk_bf16_f32 v26, v18, v19
	v_cvt_pk_bf16_f32 v25, v24, v25
	v_cvt_pk_bf16_f32 v24, v22, v23
	v_exp_f32_e32 v18, v2
	v_sub_f32_e32 v19, v5, v59
	ds_read2_b64 v[2:5], v21 offset0:48 offset1:52
	ds_read2_b64 v[42:45], v7 offset0:72 offset1:76
	v_mfma_f32_16x16x32_bf16 v[38:41], v[38:41], v[24:27], v[46:49]
	v_cvt_pk_bf16_f32 v13, v12, v13
	v_cvt_pk_bf16_f32 v12, v10, v11
	v_cvt_pk_bf16_f32 v11, v16, v17
	ds_read2_b64 v[46:49], v20 offset0:136 offset1:140
	v_cvt_pk_bf16_f32 v10, v14, v15
	ds_read2_b64 v[14:17], v0 offset0:112 offset1:116
	s_waitcnt lgkmcnt(4)
	s_waitcnt lgkmcnt(3)
	s_waitcnt lgkmcnt(2)
	s_waitcnt lgkmcnt(1)
	s_waitcnt lgkmcnt(0)
	v_mfma_f32_16x16x32_bf16 v[30:33], v[60:63], v[24:27], v[30:33]
	v_mul_f32_e32 v19, 0x3e38aa3b, v19
	v_exp_f32_e32 v19, v19
	v_mfma_f32_16x16x32_bf16 v[2:5], v[2:5], v[10:13], v[38:41]
	v_add_f32_e32 v8, v18, v8
	s_nop 1
	ds_read2_b64 v[38:41], v20 offset0:144 offset1:148
	v_mfma_f32_16x16x32_bf16 v[42:45], v[42:45], v[24:27], v[50:53]
	s_waitcnt lgkmcnt(0)
	v_mfma_f32_16x16x32_bf16 v[22:25], v[46:49], v[24:27], v[34:37]
	s_nop 2
	ds_read2_b64 v[34:37], v7 offset0:80 offset1:84
	v_mfma_f32_16x16x32_bf16 v[14:17], v[14:17], v[10:13], v[30:33]
	s_waitcnt lgkmcnt(0)
	s_nop 0
	ds_read2_b64 v[30:33], v21 offset0:56 offset1:60
	v_mfma_f32_16x16x32_bf16 v[22:25], v[38:41], v[10:13], v[22:25]
	v_cvt_pk_bf16_f32 v41, v18, v19
	v_cvt_pk_bf16_f32 v40, v9, v28
	v_cvt_pk_bf16_f32 v39, v90, v76
	s_waitcnt lgkmcnt(0)
	v_cvt_pk_bf16_f32 v38, v6, v29
	v_mfma_f32_16x16x32_bf16 v[34:37], v[34:37], v[10:13], v[42:45]
	v_add_f32_e32 v21, v19, v8
	ds_read2_b64 v[8:11], v7 offset0:88 offset1:92
	ds_read2_b64 v[26:29], v0 offset0:120 offset1:124
	v_mfma_f32_16x16x32_bf16 v[2:5], v[30:33], v[38:41], v[2:5]
	ds_read2_b64 v[30:33], v20 offset0:152 offset1:156
	ds_bpermute_b32 v0, v58, v21
	s_waitcnt lgkmcnt(3)
	s_waitcnt lgkmcnt(2)
	s_waitcnt lgkmcnt(1)
	s_waitcnt lgkmcnt(0)
	v_add_f32_e32 v0, v21, v0
	ds_bpermute_b32 v18, v57, v0
	v_mfma_f32_16x16x32_bf16 v[6:9], v[8:11], v[38:41], v[34:37]
	v_mfma_f32_16x16x32_bf16 v[10:13], v[26:29], v[38:41], v[14:17]
	v_mfma_f32_16x16x32_bf16 v[14:17], v[30:33], v[38:41], v[22:25]
	s_setprio 0
	s_cbranch_vccnz .LBB0_1351
	s_waitcnt lgkmcnt(0)
	v_add_f32_e32 v0, v0, v18
	v_div_scale_f32 v18, s[4:5], v0, v0, 1.0
	v_rcp_f32_e32 v19, v18
	v_mov_b32_e32 v57, v1
	v_lshl_add_u64 v[20:21], v[54:55], 0, v[56:57]
	v_fma_f32 v22, -v18, v19, 1.0
	v_fmac_f32_e32 v19, v22, v19
	v_div_scale_f32 v22, vcc, 1.0, v0, 1.0
	v_mul_f32_e32 v23, v22, v19
	v_fma_f32 v24, -v18, v23, v22
	v_fmac_f32_e32 v23, v24, v19
	v_fma_f32 v18, -v18, v23, v22
	v_div_fmas_f32 v18, v18, v19, v23
	v_div_fixup_f32 v0, v18, v0, 1.0
	v_pk_mul_f32 v[4:5], v[0:1], v[4:5] op_sel_hi:[0,1]
	v_pk_mul_f32 v[2:3], v[0:1], v[2:3] op_sel_hi:[0,1]
	v_cvt_pk_bf16_f32 v5, v4, v5
	v_cvt_pk_bf16_f32 v4, v2, v3
	global_store_dwordx2 v[20:21], v[4:5], off
	v_pk_mul_f32 v[2:3], v[0:1], v[8:9] op_sel_hi:[0,1]
	v_pk_mul_f32 v[4:5], v[0:1], v[6:7] op_sel_hi:[0,1]
	v_cvt_pk_bf16_f32 v3, v2, v3
	v_cvt_pk_bf16_f32 v2, v4, v5
	global_store_dwordx2 v[20:21], v[2:3], off offset:32
	v_pk_mul_f32 v[2:3], v[0:1], v[12:13] op_sel_hi:[0,1]
	v_pk_mul_f32 v[4:5], v[0:1], v[10:11] op_sel_hi:[0,1]
	v_cvt_pk_bf16_f32 v3, v2, v3
	v_cvt_pk_bf16_f32 v2, v4, v5
	global_store_dwordx2 v[20:21], v[2:3], off offset:64
	v_pk_mul_f32 v[2:3], v[0:1], v[16:17] op_sel_hi:[0,1]
	v_pk_mul_f32 v[4:5], v[0:1], v[14:15] op_sel_hi:[0,1]
	v_cvt_pk_bf16_f32 v3, v2, v3
	v_cvt_pk_bf16_f32 v2, v4, v5
	global_store_dwordx2 v[20:21], v[2:3], off offset:96

; __device__ __forceinline__ unsigned short f2bf(float f) { return (unsigned short)(pack2(f, 0.f) & 0xffffu); }
; __device__ __forceinline__ float lo2f(unsigned u) { return __uint_as_float(u << 16); }
; __device__ __forceinline__ float hi2f(unsigned u) { return __uint_as_float(u & 0xffff0000u); }
; __device__ void gmlp_item(const Params& p, int chunk, int dry) {
;     ...
;   for (int g = 0; g < 12; ++g) {
;     bf16_t* Vb = Vt + (g & 1) * (64 * 136);
; #pragma unroll
;     for (int i = 0; i < 2; ++i) {
;       const int s = ss0 + 64 * i;
;       const float2 st = stats[s];
;       const unsigned uw[4] = {gvr[i].x, gvr[i].y, gvr[i].z, gvr[i].w};
;       const float gg[8] = {lg[0].x, lg[0].y, lg[0].z, lg[0].w, lg[1].x, lg[1].y, lg[1].z, lg[1].w};
;       const float gb[8] = {lb[0].x, lb[0].y, lb[0].z, lb[0].w, lb[1].x, lb[1].y, lb[1].z, lb[1].w};
; #pragma unroll
;       for (int j = 0; j < 8; ++j) {
;         float x = (j & 1) ? hi2f(uw[j >> 1]) : lo2f(uw[j >> 1]);
;         float y = (x - st.x) * st.y * gg[j] + gb[j];
;         Vb[(d0 + j) * 136 + s] = f2bf(y);
;       }
;     }
;     __syncthreads();
.LBB0_1369:
	ds_read_b64 v[42:43], v97
	s_waitcnt vmcnt(14)
	v_lshlrev_b32_e32 v44, 16, v38
	v_and_b32_e32 v38, 0xffff0000, v38
	s_bitcmp1_b32 s8, 0
	v_lshlrev_b32_e32 v0, 1, v60
	s_waitcnt lgkmcnt(0)
	v_sub_f32_e32 v38, v38, v42
	v_mul_f32_e32 v38, v43, v38
	s_cselect_b32 s4, 0x4400, 0
	s_waitcnt vmcnt(9)
	v_fma_f32 v38, v31, v38, v35
	v_add3_u32 v0, s4, v0, v98
	v_cvt_pk_bf16_f32 v38, v38, s0
	ds_write_b16 v0, v38 offset:1296
	v_lshlrev_b32_e32 v38, 16, v39
	v_sub_f32_e32 v38, v38, v42
	v_mul_f32_e32 v38, v43, v38
	v_fma_f32 v38, v32, v38, v36
	v_cvt_pk_bf16_f32 v38, v38, s0
	ds_write_b16 v0, v38 offset:1568
	v_and_b32_e32 v38, 0xffff0000, v39
	v_sub_f32_e32 v38, v38, v42
	v_mul_f32_e32 v38, v43, v38
	v_fma_f32 v38, v33, v38, v37
	v_cvt_pk_bf16_f32 v38, v38, s0
	ds_write_b16 v0, v38 offset:1840
	v_lshlrev_b32_e32 v38, 16, v40
	v_sub_f32_e32 v38, v38, v42
	v_mul_f32_e32 v38, v43, v38
	v_fma_f32 v38, v18, v38, v26
	v_cvt_pk_bf16_f32 v38, v38, s0
	ds_write_b16 v0, v38 offset:2112
	v_and_b32_e32 v38, 0xffff0000, v40
	v_sub_f32_e32 v38, v38, v42
	v_mul_f32_e32 v38, v43, v38
	v_fma_f32 v38, v19, v38, v27
	v_cvt_pk_bf16_f32 v38, v38, s0
	ds_write_b16 v0, v38 offset:2384
	v_lshlrev_b32_e32 v38, 16, v41
	v_sub_f32_e32 v38, v38, v42
	v_mul_f32_e32 v38, v43, v38
	v_fma_f32 v38, v20, v38, v28
	v_cvt_pk_bf16_f32 v38, v38, s0
	ds_write_b16 v0, v38 offset:2656
	v_and_b32_e32 v38, 0xffff0000, v41
	v_sub_f32_e32 v44, v44, v42
	v_sub_f32_e32 v38, v38, v42
	v_mul_f32_e32 v44, v43, v44
	v_mul_f32_e32 v38, v43, v38
	v_fma_f32 v44, v30, v44, v34
	v_fma_f32 v38, v21, v38, v29
	v_cvt_pk_bf16_f32 v44, v44, s0
	v_cvt_pk_bf16_f32 v38, v38, s0
	ds_write_b16 v0, v44 offset:1024
	ds_write_b16 v0, v38 offset:2928
	ds_read_b64 v[38:39], v97 offset:512
	v_lshlrev_b32_e32 v40, 16, v14
	v_and_b32_e32 v14, 0xffff0000, v14
	s_waitcnt vmcnt(5)
	v_mov_b64_e32 v[102:103], v[4:5]
	v_mov_b64_e32 v[100:101], v[2:3]
	s_waitcnt lgkmcnt(0)
	v_sub_f32_e32 v14, v14, v38
	v_mul_f32_e32 v14, v39, v14
	v_fmac_f32_e32 v35, v31, v14
	v_cvt_pk_bf16_f32 v14, v35, s0
	ds_write_b16 v0, v14 offset:1424
	v_lshlrev_b32_e32 v14, 16, v15
	v_sub_f32_e32 v14, v14, v38
	v_mul_f32_e32 v14, v39, v14
	v_fma_f32 v14, v32, v14, v36
	v_cvt_pk_bf16_f32 v14, v14, s0
	ds_write_b16 v0, v14 offset:1696
	v_and_b32_e32 v14, 0xffff0000, v15
	v_sub_f32_e32 v14, v14, v38
	v_mul_f32_e32 v14, v39, v14
	v_fmac_f32_e32 v37, v33, v14
	v_cvt_pk_bf16_f32 v14, v37, s0
	ds_write_b16 v0, v14 offset:1968
	v_lshlrev_b32_e32 v14, 16, v16
	v_sub_f32_e32 v14, v14, v38
	v_mul_f32_e32 v14, v39, v14
	v_fma_f32 v14, v18, v14, v26
	v_cvt_pk_bf16_f32 v14, v14, s0
	ds_write_b16 v0, v14 offset:2240
	v_and_b32_e32 v14, 0xffff0000, v16
	v_sub_f32_e32 v14, v14, v38
	v_mul_f32_e32 v14, v39, v14
	v_fmac_f32_e32 v27, v19, v14
	v_cvt_pk_bf16_f32 v14, v27, s0
	ds_write_b16 v0, v14 offset:2512
	v_lshlrev_b32_e32 v14, 16, v17
	v_sub_f32_e32 v14, v14, v38
	v_mul_f32_e32 v14, v39, v14
	v_fma_f32 v14, v20, v14, v28
	v_cvt_pk_bf16_f32 v14, v14, s0
	ds_write_b16 v0, v14 offset:2784
	v_and_b32_e32 v14, 0xffff0000, v17
	v_sub_f32_e32 v40, v40, v38
	v_sub_f32_e32 v14, v14, v38
	v_mul_f32_e32 v40, v39, v40
	v_mul_f32_e32 v14, v39, v14
	v_fma_f32 v30, v30, v40, v34
	v_fmac_f32_e32 v29, v21, v14
	v_cvt_pk_bf16_f32 v30, v30, s0
	v_cvt_pk_bf16_f32 v14, v29, s0
	ds_write_b16 v0, v30 offset:1152
	ds_write_b16 v0, v14 offset:3056
	v_or_b32_e32 v0, s4, v83
	v_add_u32_e32 v0, v0, v96
	s_waitcnt lgkmcnt(0)
	s_barrier
; __device__ __forceinline__ float lo2f(unsigned u) { return __uint_as_float(u << 16); }
; __device__ __forceinline__ float hi2f(unsigned u) { return __uint_as_float(u & 0xffff0000u); }
; __device__ void gmlp_item(const Params& p, int chunk, int dry) {
;     ...
;     bf16x8 wc[4]; uint2 uc[4];
; #pragma unroll
;     for (int k = 0; k < 4; ++k) { wc[k] = wf[k]; uc[k] = uu[k]; }
;     const float bsc = bs;
;     if (g + 1 < 12) GMLP_FETCH(g + 1, gvr, lg, lb, wf, uu, bs);
;     f32x4 acc[4] = {};
; #pragma unroll
;     for (int ks = 0; ks < 4; ++ks) {
; #pragma unroll
;       for (int mt = 0; mt < 4; ++mt) {
;         bf16x8 av = *(const bf16x8*)(Vb + (mt * 16 + r) * 136 + ks * 32 + quad * 8);
;         acc[mt] = __builtin_amdgcn_mfma_f32_16x16x32_bf16(av, wc[ks], acc[mt], 0, 0, 0);
;       }
;     }
; #pragma unroll
;     for (int mt = 0; mt < 4; ++mt) {
;       bf16_t* up = cat + (size_t)(t0 + t) * 1024 + g * 64 + mt * 16 + quad * 4;
;       const uint2 u = uc[mt];
;       uint2 o;
;       o.x = pack2(lo2f(u.x) * (acc[mt][0] + bsc), hi2f(u.x) * (acc[mt][1] + bsc));
;       o.y = pack2(lo2f(u.y) * (acc[mt][2] + bsc), hi2f(u.y) * (acc[mt][3] + bsc));
;       if (!dry) *(uint2*)up = o;
;     }
	ds_read_b128 v[14:17], v0 offset:1024
	ds_read_b128 v[18:21], v0 offset:5376
	ds_read_b128 v[26:29], v0 offset:9728
	ds_read_b128 v[30:33], v0 offset:1088
	ds_read_b128 v[2:5], v0 offset:5440
	v_mov_b64_e32 v[44:45], v[8:9]
	v_mov_b64_e32 v[42:43], v[6:7]
	s_waitcnt lgkmcnt(3)
	s_setprio 1
	v_mfma_f32_16x16x32_bf16 v[6:9], v[18:21], v[22:25], 0
	ds_read_b128 v[18:21], v0 offset:14080
	ds_read_b128 v[34:37], v0 offset:9792
	v_lshl_add_u64 v[38:39], s[14:15], 0, v[72:73]
	v_add_co_u32_e32 v38, vcc, s37, v38
	v_mfma_f32_16x16x32_bf16 v[14:17], v[14:17], v[22:25], 0
	s_nop 0
	v_addc_co_u32_e32 v39, vcc, 0, v39, vcc
	v_lshl_add_u64 v[40:41], s[14:15], 0, v[74:75]
	s_waitcnt lgkmcnt(4)
	v_mfma_f32_16x16x32_bf16 v[26:29], v[26:29], v[22:25], 0
	ds_read_b128 v[46:49], v0 offset:14144
	s_mov_b32 s4, 0x2f88000
	v_cndmask_b32_e64 v61, 0, 1, s[24:25]
	s_waitcnt lgkmcnt(2)
	v_mfma_f32_16x16x32_bf16 v[22:25], v[18:21], v[22:25], 0
	v_add_co_u32_e32 v18, vcc, s37, v40
	s_nop 1
	v_addc_co_u32_e32 v19, vcc, 0, v41, vcc
	v_mfma_f32_16x16x32_bf16 v[50:53], v[30:33], v[10:13], v[14:17]
	v_lshl_add_u64 v[30:31], v[62:63], 0, s[6:7]
	global_load_dwordx4 v[38:41], v[38:39], off offset:128
	s_nop 0
	global_load_dwordx4 v[14:17], v[18:19], off offset:128
	s_nop 0
	global_load_dwordx4 v[18:21], v[30:31], off offset:272
	s_nop 0
	global_load_dwordx4 v[30:33], v[30:31], off offset:256
	v_mfma_f32_16x16x32_bf16 v[2:5], v[2:5], v[10:13], v[6:9]
	s_nop 2
	ds_read_b128 v[6:9], v0 offset:1152
	s_waitcnt lgkmcnt(2)
	v_mfma_f32_16x16x32_bf16 v[54:57], v[34:37], v[10:13], v[26:29]
	v_lshl_add_u64 v[34:35], v[64:65], 0, s[6:7]
	s_nop 1
	global_load_dwordx4 v[26:29], v[34:35], off offset:272
	s_nop 0
	global_load_dwordx4 v[34:37], v[34:35], off offset:256
	s_waitcnt lgkmcnt(1)
	v_mfma_f32_16x16x32_bf16 v[46:49], v[46:49], v[10:13], v[22:25]
	ds_read_b128 v[10:13], v0 offset:5504
	ds_read_b128 v[76:79], v0 offset:1216
	ds_read_b128 v[104:107], v0 offset:5568
	v_lshl_add_u64 v[22:23], s[14:15], 0, v[66:67]
	s_waitcnt lgkmcnt(3)
	v_mfma_f32_16x16x32_bf16 v[50:53], v[6:9], v[42:45], v[50:53]
	ds_read_b128 v[6:9], v0 offset:9856
	v_add_co_u32_e32 v84, vcc, s4, v22
	s_waitcnt lgkmcnt(0)
	v_mfma_f32_16x16x32_bf16 v[120:123], v[6:9], v[42:45], v[54:57]
	v_addc_co_u32_e32 v85, vcc, 0, v23, vcc
	s_nop 1
	v_lshl_add_u64 v[54:55], s[14:15], 0, v[68:69]
	s_mov_b32 s4, 0xe1a6000
	v_add_co_u32_e32 v94, vcc, s4, v54
	v_mfma_f32_16x16x32_bf16 v[108:111], v[10:13], v[42:45], v[2:5]
	s_nop 0
	v_addc_co_u32_e32 v95, vcc, 0, v55, vcc
	ds_read_b128 v[112:115], v0 offset:14208
	global_load_dwordx4 v[22:25], v[84:85], off
	global_load_dwordx4 v[10:13], v[84:85], off offset:64
	ds_read_b128 v[116:119], v0 offset:9920
	global_load_dwordx4 v[6:9], v[84:85], off offset:128
	global_load_dwordx4 v[2:5], v[84:85], off offset:192
	ds_read_b128 v[124:127], v0 offset:14272
	v_mfma_f32_16x16x32_bf16 v[54:57], v[76:79], v[100:103], v[50:53]
	global_load_dwordx2 v[88:89], v[94:95], off offset:128
	global_load_dwordx2 v[84:85], v[94:95], off offset:160
	global_load_dwordx2 v[78:79], v[94:95], off offset:192
	global_load_dwordx2 v[76:77], v[94:95], off offset:224
	global_load_dword v0, v[70:71], off
	v_cmp_ne_u32_e64 s[4:5], 1, v61
	s_waitcnt lgkmcnt(2)
	v_mfma_f32_16x16x32_bf16 v[42:45], v[112:115], v[42:45], v[46:49]
	s_andn2_b64 vcc, exec, s[24:25]
	v_mfma_f32_16x16x32_bf16 v[46:49], v[104:107], v[100:103], v[108:111]
	s_waitcnt lgkmcnt(1)
	v_mfma_f32_16x16x32_bf16 v[50:53], v[116:119], v[100:103], v[120:123]
	s_waitcnt lgkmcnt(0)
	v_mfma_f32_16x16x32_bf16 v[42:45], v[124:127], v[100:103], v[42:45]
	s_setprio 0
	s_cbranch_vccnz .LBB0_1371
	s_waitcnt vmcnt(19)
	v_lshlrev_b32_e32 v100, 16, v93
	v_and_b32_e32 v101, 0xffff0000, v93
	s_waitcnt vmcnt(15)
	v_pk_add_f32 v[56:57], v[82:83], v[56:57] op_sel_hi:[0,1]
	v_pk_mul_f32 v[56:57], v[56:57], v[100:101]
	v_lshlrev_b32_e32 v100, 16, v92
	v_and_b32_e32 v101, 0xffff0000, v92
	v_pk_add_f32 v[54:55], v[82:83], v[54:55] op_sel_hi:[0,1]
	v_pk_mul_f32 v[54:55], v[54:55], v[100:101]
	v_cvt_pk_bf16_f32 v57, v56, v57
	v_cvt_pk_bf16_f32 v56, v54, v55
	v_lshlrev_b32_e32 v54, 16, v91
	v_and_b32_e32 v55, 0xffff0000, v91
	v_pk_add_f32 v[48:49], v[82:83], v[48:49] op_sel_hi:[0,1]
	v_pk_mul_f32 v[48:49], v[48:49], v[54:55]
	v_lshlrev_b32_e32 v54, 16, v90
	v_and_b32_e32 v55, 0xffff0000, v90
	v_pk_add_f32 v[46:47], v[82:83], v[46:47] op_sel_hi:[0,1]
	v_pk_mul_f32 v[46:47], v[46:47], v[54:55]
	v_cvt_pk_bf16_f32 v49, v48, v49
	v_cvt_pk_bf16_f32 v48, v46, v47
	global_store_dwordx2 v[94:95], v[48:49], off offset:32
	v_lshlrev_b32_e32 v46, 16, v87
	v_and_b32_e32 v47, 0xffff0000, v87
	v_pk_add_f32 v[48:49], v[82:83], v[52:53] op_sel_hi:[0,1]
	v_pk_mul_f32 v[46:47], v[48:49], v[46:47]
	v_lshlrev_b32_e32 v48, 16, v86
	v_and_b32_e32 v49, 0xffff0000, v86
	v_pk_add_f32 v[50:51], v[82:83], v[50:51] op_sel_hi:[0,1]
	v_pk_mul_f32 v[48:49], v[50:51], v[48:49]
	v_cvt_pk_bf16_f32 v47, v46, v47
	v_cvt_pk_bf16_f32 v46, v48, v49
	global_store_dwordx2 v[94:95], v[46:47], off offset:64
	v_lshlrev_b32_e32 v46, 16, v81
	v_and_b32_e32 v47, 0xffff0000, v81
	v_pk_add_f32 v[44:45], v[82:83], v[44:45] op_sel_hi:[0,1]
	v_pk_mul_f32 v[44:45], v[44:45], v[46:47]
	v_lshlrev_b32_e32 v46, 16, v80
	v_and_b32_e32 v47, 0xffff0000, v80
	v_pk_add_f32 v[42:43], v[82:83], v[42:43] op_sel_hi:[0,1]
	v_pk_mul_f32 v[42:43], v[42:43], v[46:47]
	v_cvt_pk_bf16_f32 v45, v44, v45
	v_cvt_pk_bf16_f32 v44, v42, v43
	global_store_dwordx2 v[94:95], v[56:57], off
	global_store_dwordx2 v[94:95], v[44:45], off offset:96

; __device__ __forceinline__ unsigned short f2bf(float f) { return (unsigned short)(pack2(f, 0.f) & 0xffffu); }
; __device__ __forceinline__ float lo2f(unsigned u) { return __uint_as_float(u << 16); }
; __device__ __forceinline__ float hi2f(unsigned u) { return __uint_as_float(u & 0xffff0000u); }
; __device__ void gmlp_item(const Params& p, int chunk, int dry) {
;     ...
; #pragma unroll
;     for (int i = 0; i < 2; ++i) {
;       const int s = ss0 + 64 * i;
;       const float2 st = stats[s];
;       const unsigned uw[4] = {gvr[i].x, gvr[i].y, gvr[i].z, gvr[i].w};
;       const float gg[8] = {lg[0].x, lg[0].y, lg[0].z, lg[0].w, lg[1].x, lg[1].y, lg[1].z, lg[1].w};
;       const float gb[8] = {lb[0].x, lb[0].y, lb[0].z, lb[0].w, lb[1].x, lb[1].y, lb[1].z, lb[1].w};
; #pragma unroll
;       for (int j = 0; j < 8; ++j) {
;         float x = (j & 1) ? hi2f(uw[j >> 1]) : lo2f(uw[j >> 1]);
;         float y = (x - st.x) * st.y * gg[j] + gb[j];
;         Vb[(d0 + j) * 136 + s] = f2bf(y);
;       }
;     }
;     __syncthreads();
.LBB0_1373:
	ds_read_b64 v[42:43], v97
	s_waitcnt vmcnt(14)
	v_lshlrev_b32_e32 v44, 16, v38
	v_and_b32_e32 v38, 0xffff0000, v38
	v_lshl_add_u32 v45, v60, 1, v98
	s_and_b64 vcc, exec, s[4:5]
	s_waitcnt lgkmcnt(0)
	v_sub_f32_e32 v38, v38, v42
	v_mul_f32_e32 v38, v43, v38
	s_waitcnt vmcnt(9)
	v_fma_f32 v38, v31, v38, v35
	v_cvt_pk_bf16_f32 v38, v38, s0
	ds_write_b16 v45, v38 offset:18704
	v_lshlrev_b32_e32 v38, 16, v39
	v_sub_f32_e32 v38, v38, v42
	v_mul_f32_e32 v38, v43, v38
	v_fma_f32 v38, v32, v38, v36
	v_cvt_pk_bf16_f32 v38, v38, s0
	ds_write_b16 v45, v38 offset:18976
	v_and_b32_e32 v38, 0xffff0000, v39
	v_sub_f32_e32 v38, v38, v42
	v_mul_f32_e32 v38, v43, v38
	v_fma_f32 v38, v33, v38, v37
	v_cvt_pk_bf16_f32 v38, v38, s0
	ds_write_b16 v45, v38 offset:19248
	v_lshlrev_b32_e32 v38, 16, v40
	v_sub_f32_e32 v38, v38, v42
	v_mul_f32_e32 v38, v43, v38
	v_fma_f32 v38, v18, v38, v26
	v_cvt_pk_bf16_f32 v38, v38, s0
	ds_write_b16 v45, v38 offset:19520
	v_and_b32_e32 v38, 0xffff0000, v40
	v_sub_f32_e32 v38, v38, v42
	v_mul_f32_e32 v38, v43, v38
	v_fma_f32 v38, v19, v38, v27
	v_cvt_pk_bf16_f32 v38, v38, s0
	ds_write_b16 v45, v38 offset:19792
	v_lshlrev_b32_e32 v38, 16, v41
	v_sub_f32_e32 v38, v38, v42
	v_mul_f32_e32 v38, v43, v38
	v_fma_f32 v38, v20, v38, v28
	v_cvt_pk_bf16_f32 v38, v38, s0
	ds_write_b16 v45, v38 offset:20064
	v_and_b32_e32 v38, 0xffff0000, v41
	v_sub_f32_e32 v44, v44, v42
	v_sub_f32_e32 v38, v38, v42
	v_mul_f32_e32 v44, v43, v44
	v_mul_f32_e32 v38, v43, v38
	v_fma_f32 v44, v30, v44, v34
	v_fma_f32 v38, v21, v38, v29
	v_cvt_pk_bf16_f32 v44, v44, s0
	v_cvt_pk_bf16_f32 v38, v38, s0
	ds_write_b16 v45, v44 offset:18432
	ds_write_b16 v45, v38 offset:20336
	ds_read_b64 v[38:39], v97 offset:512
	v_lshlrev_b32_e32 v40, 16, v14
	v_and_b32_e32 v14, 0xffff0000, v14
	s_waitcnt lgkmcnt(0)
	v_sub_f32_e32 v14, v14, v38
	v_mul_f32_e32 v14, v39, v14
	v_fma_f32 v14, v31, v14, v35
	v_cvt_pk_bf16_f32 v14, v14, s0
	ds_write_b16 v45, v14 offset:18832
	v_lshlrev_b32_e32 v14, 16, v15
	v_sub_f32_e32 v14, v14, v38
	v_mul_f32_e32 v14, v39, v14
	v_fma_f32 v14, v32, v14, v36
	v_cvt_pk_bf16_f32 v14, v14, s0
	ds_write_b16 v45, v14 offset:19104
	v_and_b32_e32 v14, 0xffff0000, v15
	v_sub_f32_e32 v14, v14, v38
	v_mul_f32_e32 v14, v39, v14
	v_fmac_f32_e32 v37, v33, v14
	v_cvt_pk_bf16_f32 v14, v37, s0
	ds_write_b16 v45, v14 offset:19376
	v_lshlrev_b32_e32 v14, 16, v16
	v_sub_f32_e32 v14, v14, v38
	v_mul_f32_e32 v14, v39, v14
	v_fma_f32 v14, v18, v14, v26
	v_cvt_pk_bf16_f32 v14, v14, s0
	ds_write_b16 v45, v14 offset:19648
	v_and_b32_e32 v14, 0xffff0000, v16
	v_sub_f32_e32 v14, v14, v38
	v_mul_f32_e32 v14, v39, v14
	v_fma_f32 v14, v19, v14, v27
	v_cvt_pk_bf16_f32 v14, v14, s0
	ds_write_b16 v45, v14 offset:19920
	v_lshlrev_b32_e32 v14, 16, v17
	v_sub_f32_e32 v14, v14, v38
	v_mul_f32_e32 v14, v39, v14
	v_fma_f32 v14, v20, v14, v28
	v_cvt_pk_bf16_f32 v14, v14, s0
	ds_write_b16 v45, v14 offset:20192
	v_and_b32_e32 v14, 0xffff0000, v17
	v_sub_f32_e32 v40, v40, v38
	v_sub_f32_e32 v14, v14, v38
	v_mul_f32_e32 v40, v39, v40
	v_mul_f32_e32 v14, v39, v14
	v_fma_f32 v30, v30, v40, v34
	v_fmac_f32_e32 v29, v21, v14
	v_cvt_pk_bf16_f32 v30, v30, s0
	v_cvt_pk_bf16_f32 v14, v29, s0
	v_add_u32_e32 v34, v83, v96
	ds_write_b16 v45, v30 offset:18560
	ds_write_b16 v45, v14 offset:20464
	s_waitcnt lgkmcnt(0)
	s_barrier
; __device__ __forceinline__ float lo2f(unsigned u) { return __uint_as_float(u << 16); }
; __device__ __forceinline__ float hi2f(unsigned u) { return __uint_as_float(u & 0xffff0000u); }
; __device__ void gmlp_item(const Params& p, int chunk, int dry) {
;     ...
;     f32x4 acc[4] = {};
; #pragma unroll
;     for (int ks = 0; ks < 4; ++ks) {
; #pragma unroll
;       for (int mt = 0; mt < 4; ++mt) {
;         bf16x8 av = *(const bf16x8*)(Vb + (mt * 16 + r) * 136 + ks * 32 + quad * 8);
;         acc[mt] = __builtin_amdgcn_mfma_f32_16x16x32_bf16(av, wc[ks], acc[mt], 0, 0, 0);
;       }
;     }
; #pragma unroll
;     for (int mt = 0; mt < 4; ++mt) {
;       bf16_t* up = cat + (size_t)(t0 + t) * 1024 + g * 64 + mt * 16 + quad * 4;
;       const uint2 u = uc[mt];
;       uint2 o;
;       o.x = pack2(lo2f(u.x) * (acc[mt][0] + bsc), hi2f(u.x) * (acc[mt][1] + bsc));
;       o.y = pack2(lo2f(u.y) * (acc[mt][2] + bsc), hi2f(u.y) * (acc[mt][3] + bsc));
;       if (!dry) *(uint2*)up = o;
;     }
	ds_read_b128 v[14:17], v34 offset:18432
	ds_read_b128 v[18:21], v34 offset:22784
	ds_read_b128 v[26:29], v34 offset:27136
	ds_read_b128 v[30:33], v34 offset:31488
	s_waitcnt vmcnt(8) lgkmcnt(3)
	s_setprio 1
	v_mfma_f32_16x16x32_bf16 v[14:17], v[14:17], v[22:25], 0
	s_waitcnt lgkmcnt(2)
	v_mfma_f32_16x16x32_bf16 v[18:21], v[18:21], v[22:25], 0
	s_waitcnt lgkmcnt(1)
	v_mfma_f32_16x16x32_bf16 v[26:29], v[26:29], v[22:25], 0
	s_waitcnt lgkmcnt(0)
	v_mfma_f32_16x16x32_bf16 v[22:25], v[30:33], v[22:25], 0
	ds_read_b128 v[30:33], v34 offset:18496
	s_waitcnt vmcnt(7) lgkmcnt(0)
	v_mfma_f32_16x16x32_bf16 v[14:17], v[30:33], v[10:13], v[14:17]
	ds_read_b128 v[30:33], v34 offset:22848
	s_waitcnt lgkmcnt(0)
	v_mfma_f32_16x16x32_bf16 v[18:21], v[30:33], v[10:13], v[18:21]
	ds_read_b128 v[30:33], v34 offset:27200
	s_waitcnt lgkmcnt(0)
	v_mfma_f32_16x16x32_bf16 v[26:29], v[30:33], v[10:13], v[26:29]
	ds_read_b128 v[30:33], v34 offset:31552
	s_waitcnt lgkmcnt(0)
	v_mfma_f32_16x16x32_bf16 v[10:13], v[30:33], v[10:13], v[22:25]
	s_nop 2
	ds_read_b128 v[22:25], v34 offset:18560
	s_waitcnt vmcnt(6) lgkmcnt(0)
	v_mfma_f32_16x16x32_bf16 v[14:17], v[22:25], v[6:9], v[14:17]
	ds_read_b128 v[22:25], v34 offset:22912
	s_waitcnt lgkmcnt(0)
	v_mfma_f32_16x16x32_bf16 v[18:21], v[22:25], v[6:9], v[18:21]
	ds_read_b128 v[22:25], v34 offset:27264
	s_waitcnt lgkmcnt(0)
	v_mfma_f32_16x16x32_bf16 v[22:25], v[22:25], v[6:9], v[26:29]
	s_nop 2
	ds_read_b128 v[26:29], v34 offset:31616
	s_waitcnt lgkmcnt(0)
	v_mfma_f32_16x16x32_bf16 v[26:29], v[26:29], v[6:9], v[10:13]
	ds_read_b128 v[6:9], v34 offset:18624
	s_waitcnt vmcnt(5) lgkmcnt(0)
	v_mfma_f32_16x16x32_bf16 v[14:17], v[6:9], v[2:5], v[14:17]
	ds_read_b128 v[6:9], v34 offset:22976
	s_waitcnt lgkmcnt(0)
	v_mfma_f32_16x16x32_bf16 v[10:13], v[6:9], v[2:5], v[18:21]
	ds_read_b128 v[6:9], v34 offset:27328
	s_nop 1
	ds_read_b128 v[18:21], v34 offset:31680
	s_waitcnt lgkmcnt(1)
	v_mfma_f32_16x16x32_bf16 v[6:9], v[6:9], v[2:5], v[22:25]
	s_waitcnt lgkmcnt(0)
	v_mfma_f32_16x16x32_bf16 v[2:5], v[18:21], v[2:5], v[26:29]
	s_setprio 0
	s_cbranch_vccnz .LBB0_1306
	s_waitcnt vmcnt(4)
	v_lshlrev_b32_e32 v18, 16, v89
	v_and_b32_e32 v19, 0xffff0000, v89
	s_waitcnt vmcnt(0)
	v_pk_add_f32 v[16:17], v[0:1], v[16:17] op_sel_hi:[0,1]
	v_pk_mul_f32 v[16:17], v[16:17], v[18:19]
	v_lshlrev_b32_e32 v18, 16, v88
	v_and_b32_e32 v19, 0xffff0000, v88
	v_pk_add_f32 v[14:15], v[0:1], v[14:15] op_sel_hi:[0,1]
	v_pk_mul_f32 v[14:15], v[14:15], v[18:19]
	v_cvt_pk_bf16_f32 v17, v16, v17
	v_cvt_pk_bf16_f32 v16, v14, v15
	v_lshlrev_b32_e32 v14, 16, v85
	v_and_b32_e32 v15, 0xffff0000, v85
	v_pk_add_f32 v[12:13], v[0:1], v[12:13] op_sel_hi:[0,1]
	v_pk_mul_f32 v[12:13], v[12:13], v[14:15]
	v_lshlrev_b32_e32 v14, 16, v84
	v_and_b32_e32 v15, 0xffff0000, v84
	v_pk_add_f32 v[10:11], v[0:1], v[10:11] op_sel_hi:[0,1]
	v_pk_mul_f32 v[10:11], v[10:11], v[14:15]
	v_cvt_pk_bf16_f32 v13, v12, v13
	v_cvt_pk_bf16_f32 v12, v10, v11
	v_lshlrev_b32_e32 v10, 16, v79
	v_and_b32_e32 v11, 0xffff0000, v79
	v_pk_add_f32 v[8:9], v[0:1], v[8:9] op_sel_hi:[0,1]
	v_pk_mul_f32 v[8:9], v[8:9], v[10:11]
	v_lshlrev_b32_e32 v10, 16, v78
	v_and_b32_e32 v11, 0xffff0000, v78
	v_pk_add_f32 v[6:7], v[0:1], v[6:7] op_sel_hi:[0,1]
	v_pk_mul_f32 v[6:7], v[6:7], v[10:11]
	v_cvt_pk_bf16_f32 v9, v8, v9
	v_cvt_pk_bf16_f32 v8, v6, v7
	v_lshlrev_b32_e32 v6, 16, v77
	v_and_b32_e32 v7, 0xffff0000, v77
	v_pk_add_f32 v[4:5], v[0:1], v[4:5] op_sel_hi:[0,1]
	v_pk_mul_f32 v[4:5], v[4:5], v[6:7]
	v_lshlrev_b32_e32 v6, 16, v76
	v_and_b32_e32 v7, 0xffff0000, v76
	v_pk_add_f32 v[2:3], v[0:1], v[2:3] op_sel_hi:[0,1]
	v_pk_mul_f32 v[2:3], v[2:3], v[6:7]
	v_cvt_pk_bf16_f32 v5, v4, v5
	v_cvt_pk_bf16_f32 v4, v2, v3
	global_store_dwordx2 v[58:59], v[16:17], off offset:1408
	global_store_dwordx2 v[58:59], v[12:13], off offset:1440
	global_store_dwordx2 v[58:59], v[8:9], off offset:1472
	global_store_dwordx2 v[58:59], v[4:5], off offset:1504
	s_branch .LBB0_1306
